# waves 4-7 enter the S5 scan phases ~400 cycles late (stagger), on top of the no-setprio stack
# speedup vs baseline: 1.0072x; 1.0072x over previous
.LBB0_194:
	s_andn2_b64 vcc, exec, s[2:3]
	s_cbranch_vccnz .LBB0_224
	s_cmp_lt_u32 s73, 4
	s_cbranch_scc1 .Lscan_nostagger
	s_sleep 6
.Lscan_nostagger:
	s_cmp_gt_i32 s61, 7
	s_mov_b64 s[2:3], -1
	s_cbranch_scc0 .LBB0_211
	v_readlane_b32 s2, v254, 46
	v_readlane_b32 s3, v254, 47
	v_mov_b32_e32 v151, v242
	s_andn2_b64 vcc, exec, s[2:3]
	s_cbranch_vccnz .LBB0_210
	s_load_dwordx16 s[4:19], s[22:23], 0x70
	v_ashrrev_i32_e32 v6, 4, v151
	v_lshlrev_b32_e32 v155, 5, v6
	v_lshlrev_b32_e32 v4, 2, v6
	v_readlane_b32 s37, v254, 19
	s_waitcnt lgkmcnt(0)
	v_mov_b32_e32 v2, s18
	v_mov_b32_e32 v3, s19
	v_and_b32_e32 v184, 32, v155
	v_ashrrev_i32_e32 v5, 31, v4
	v_lshlrev_b32_e32 v0, 3, v6
	v_and_b32_e32 v136, 15, v151
	v_lshl_add_u64 v[142:143], s[10:11], 0, v[184:185]
	v_lshl_add_u64 v[146:147], v[4:5], 2, v[2:3]
	v_mov_b32_e32 v2, s37
	s_movk_i32 s10, 0x210
	v_ashrrev_i32_e32 v1, 31, v0
	v_mad_u32_u24 v157, v136, s10, v2
	v_lshlrev_b32_e32 v2, 8, v136
	v_mov_b32_e32 v3, v185
	v_lshlrev_b32_e32 v138, 2, v151
	v_lshlrev_b32_e32 v8, 6, v136
	v_cmp_gt_i32_e64 s[2:3], 2, v6
	v_lshl_add_u64 v[6:7], s[14:15], 0, v[2:3]
	v_lshl_add_u64 v[2:3], s[16:17], 0, v[2:3]
	v_lshlrev_b64 v[0:1], 2, v[0:1]
	s_lshl_b32 s10, s54, 3
	v_ashrrev_i32_e32 v139, 31, v138
	v_lshl_add_u64 v[144:145], s[12:13], 0, v[184:185]
	v_lshlrev_b32_e32 v148, 1, v151
	v_lshlrev_b32_e32 v9, 4, v151
	v_and_b32_e32 v198, -16, v151
	v_mul_i32_i24_e32 v10, 0xfffffdf4, v136
	v_lshlrev_b32_e32 v150, 4, v136
	v_lshl_add_u64 v[158:159], v[6:7], 0, v[0:1]
	v_lshl_add_u64 v[160:161], v[2:3], 0, v[0:1]
	s_add_i32 s31, s73, s10
	v_readlane_b32 s10, v254, 20
	v_or_b32_e32 v0, v8, v184
	v_mov_b32_e32 v184, v185
	v_lshl_add_u64 v[140:141], v[138:139], 2, s[24:25]
	v_add_u32_e32 v153, s37, v138
	v_ashrrev_i32_e32 v149, 31, v148
	v_mov_b32_e32 v137, v185
	v_or_b32_e32 v152, 0x100, v150
	v_or_b32_e32 v154, 0x200, v150
	v_or_b32_e32 v156, 0x300, v150
	v_lshl_add_u64 v[162:163], v[4:5], 1, s[38:39]
	v_add3_u32 v199, v8, v198, s10
	v_add_u32_e32 v200, s10, v0
	v_mov_b32_e32 v128, v185
	v_mov_b32_e32 v129, v185
	v_mov_b32_e32 v130, v185
	v_mov_b32_e32 v131, v185
	s_mov_b64 s[18:19], 0
	v_mov_b32_e32 v203, 0
	s_mov_b32 s39, -1
	v_add_u32_e32 v201, v157, v10
	v_add_u32_e32 v202, s37, v9
	v_mov_b32_e32 v204, 0
	s_mov_b32 s37, s30
	v_mov_b64_e32 v[164:165], v[184:185]
